# sample-row tiles of the merge GEMMs (phase 4a round 2) are handed out as tickets of the attention phase, gated on a release-acquire counter of the 8 sample attention items; phase 4a itself no longer h
# speedup vs baseline: 1.1029x; 1.0323x over previous
_Z10fwd_kernelILin1EEv6Params:
	s_mov_b32 s101, 0
	s_load_dword s3, s[0:1], 0x9c
	s_add_u32 s6, s0, 0x8a0
	s_addc_u32 s7, s1, 0
	s_waitcnt lgkmcnt(0)
	s_cmp_lt_i32 s3, 0
	s_cbranch_scc1 .LBB0_2
	v_and_b32_e32 v218, 0x3ff, v0
	s_load_dwordx2 s[38:39], s[0:1], 0x90
	s_load_dword s33, s[0:1], 0x8a0
	s_cbranch_execz .LBB0_3
	s_branch .LBB0_14

.Lp3_setup:
	s_add_u32 s4, s38, 0x6000000
	s_addc_u32 s5, s39, 0
	s_mov_b32 s43, 0
	s_add_u32 s40, s38, 0x6500000
	s_mov_b32 s3, s43
	s_addc_u32 s41, s39, 0
	s_lshl_b64 s[6:7], s[2:3], 3
	s_add_u32 s3, s0, s6
	s_addc_u32 s67, s1, s7
	s_cmpk_lg_i32 s33, 0x100
	s_cselect_b64 s[44:45], -1, 0
	s_add_u32 s46, s38, 0x2080000
	s_addc_u32 s47, s39, 0
	s_add_u32 s48, s38, 0x57c0000
	s_addc_u32 s49, s39, 0
	s_add_u32 s50, s38, 0x67a8000
	s_addc_u32 s51, s39, 0
	s_add_u32 s52, s38, 0x77e8000
	s_movk_i32 s68, 0x100
	s_addc_u32 s53, s39, 0
	v_mov_b32_e32 v1, 0
	s_movk_i32 s69, 0xa00
	s_movk_i32 s70, 0xa0
	s_movk_i32 s71, 0x140
	s_mov_b64 s[54:55], 0x2800
	s_movk_i32 s72, 0x2000
	s_mov_b64 s[56:57], 0x100
	s_movk_i32 s73, 0x800
	s_mov_b64 s[58:59], 0x5100
	s_mov_b64 s[60:61], 0x5000
	s_movk_i32 s74, 0x1000
	s_movk_i32 s75, 0x3000
	v_mov_b32_e32 v164, 0xf149f2ca
	v_mbcnt_hi_u32_b32 v197, -1, v214
	s_mov_b32 s42, s43
	s_bfe_u32 s10, s83, 0x10001
	s_lshl_b32 s10, s10, 8
	s_addk_i32 s10, 0x3700
	s_and_saveexec_b64 s[6:7], s[80:81]
	s_cbranch_execz .Lq_init_done
	v_mov_b32_e32 v2, s10
	v_mov_b32_e32 v3, 1
	global_atomic_add v215, v2, v3, s[78:79] sc0
	s_waitcnt vmcnt(0)
	v_mov_b32_e32 v2, 0xf000
	ds_write_b32 v2, v215
	s_waitcnt lgkmcnt(0)

.LBB0_474:
	s_andn2_b64 vcc, exec, s[8:9]
	s_cbranch_vccnz .LBB0_477
	s_barrier
	v_mov_b32_e32 v0, 0xf000
	ds_read_b32 v0, v0
	s_waitcnt lgkmcnt(0)
	v_readfirstlane_b32 s14, v0
	s_bfe_u32 s11, s83, 0x10001
	s_cmpk_lt_u32 s14, 0x106
	s_cselect_b64 s[6:7], -1, 0
	s_cmp_lt_u32 s14, 4
	s_cbranch_scc0 .Lq_nottiny
	s_lshl_b32 s11, s11, 8
	s_or_b32 s14, s14, s11
	s_branch .Lq_done
.Lq_nottiny:
	s_cmp_lt_u32 s14, 8
	s_cbranch_scc0 .Lq_notsmp
	s_lshl_b32 s10, s11, 2
	s_add_i32 s14, s14, s10
	s_addk_i32 s14, 0x1fc
	s_branch .Lq_done
.Lq_notsmp:
	s_add_i32 s14, s14, -8
	s_cmpk_lt_u32 s14, 0xea
	s_cbranch_scc1 .Lq_prompt
	s_cmpk_lt_u32 s14, 0xec
	s_cbranch_scc0 .Lq_late
	s_addk_i32 s14, 0xff16
	s_lshl_b32 s10, s11, 1
	s_add_i32 s100, s14, s10
	s_and_b64 vcc, exec, s[6:7]
	s_cbranch_vccnz .Le4a_call
	s_branch .Lq_done
.Lq_late:
	s_add_i32 s14, s14, -2

.Lat3_epi_a:
	v_mov_b32_e32 v15, v175
	s_nop 1
	v_permlane32_swap_b32_e32 v175, v15
	v_add_f32_e32 v175, v175, v15
	v_div_scale_f32 v2, s[16:17], v175, v175, 1.0
	v_div_scale_f32 v4, vcc, 1.0, v175, 1.0
	v_rcp_f32_e32 v3, v2
	s_nop 1
	v_fma_f32 v5, -v2, v3, 1.0
	v_fmac_f32_e32 v3, v5, v3
	v_mul_f32_e32 v5, v4, v3
	v_fma_f32 v213, -v2, v5, v4
	v_fmac_f32_e32 v5, v213, v3
	v_fma_f32 v2, -v2, v5, v4
	v_div_fmas_f32 v2, v2, v3, v5
	v_div_fixup_f32 v0, v2, v175, 1.0
	s_nop 4
	v_mul_f32_e32 v64, v64, v0
	v_mul_f32_e32 v65, v65, v0
	v_mul_f32_e32 v66, v66, v0
	v_mul_f32_e32 v67, v67, v0
	v_mul_f32_e32 v68, v68, v0
	v_mul_f32_e32 v69, v69, v0
	v_mul_f32_e32 v70, v70, v0
	v_mul_f32_e32 v71, v71, v0
	v_cvt_pk_bf16_f32 v6, v64, v65
	v_cvt_pk_bf16_f32 v7, v66, v67
	v_cvt_pk_bf16_f32 v8, v68, v69
	v_cvt_pk_bf16_f32 v9, v70, v71
	s_nop 1
	s_waitcnt vmcnt(23)
	v_mfma_f32_32x32x16_bf16 v[232:247], v[148:151], v[6:9], 0
	s_waitcnt vmcnt(22)
	v_mfma_f32_32x32x16_bf16 v[96:111], v[144:147], v[6:9], 0
	v_mul_f32_e32 v72, v72, v0
	v_mul_f32_e32 v73, v73, v0
	v_mul_f32_e32 v74, v74, v0
	v_mul_f32_e32 v75, v75, v0
	v_mul_f32_e32 v76, v76, v0
	v_mul_f32_e32 v77, v77, v0
	v_mul_f32_e32 v78, v78, v0
	v_mul_f32_e32 v79, v79, v0
	v_cvt_pk_bf16_f32 v10, v72, v73
	v_cvt_pk_bf16_f32 v11, v74, v75
	v_cvt_pk_bf16_f32 v12, v76, v77
	v_cvt_pk_bf16_f32 v13, v78, v79
	s_nop 1
	s_waitcnt vmcnt(21)
	v_mfma_f32_32x32x16_bf16 v[232:247], v[140:143], v[10:13], v[232:247]
	s_waitcnt vmcnt(20)
	v_mfma_f32_32x32x16_bf16 v[96:111], v[136:139], v[10:13], v[96:111]
	v_mul_f32_e32 v48, v48, v0
	v_mul_f32_e32 v49, v49, v0
	v_mul_f32_e32 v50, v50, v0
	v_mul_f32_e32 v51, v51, v0
	v_mul_f32_e32 v52, v52, v0
	v_mul_f32_e32 v53, v53, v0
	v_mul_f32_e32 v54, v54, v0
	v_mul_f32_e32 v55, v55, v0
	v_cvt_pk_bf16_f32 v6, v48, v49
	v_cvt_pk_bf16_f32 v7, v50, v51
	v_cvt_pk_bf16_f32 v8, v52, v53
	v_cvt_pk_bf16_f32 v9, v54, v55
	s_nop 1
	s_waitcnt vmcnt(19)
	v_mfma_f32_32x32x16_bf16 v[232:247], v[132:135], v[6:9], v[232:247]
	s_waitcnt vmcnt(18)
	v_mfma_f32_32x32x16_bf16 v[96:111], v[128:131], v[6:9], v[96:111]
	v_mul_f32_e32 v56, v56, v0
	v_mul_f32_e32 v57, v57, v0
	v_mul_f32_e32 v58, v58, v0
	v_mul_f32_e32 v59, v59, v0
	v_mul_f32_e32 v60, v60, v0
	v_mul_f32_e32 v61, v61, v0
	v_mul_f32_e32 v62, v62, v0
	v_mul_f32_e32 v63, v63, v0
	v_cvt_pk_bf16_f32 v10, v56, v57
	v_cvt_pk_bf16_f32 v11, v58, v59
	v_cvt_pk_bf16_f32 v12, v60, v61
	v_cvt_pk_bf16_f32 v13, v62, v63
	s_nop 1
	s_waitcnt vmcnt(17)
	v_mfma_f32_32x32x16_bf16 v[232:247], v[124:127], v[10:13], v[232:247]
	s_waitcnt vmcnt(16)
	v_mfma_f32_32x32x16_bf16 v[96:111], v[120:123], v[10:13], v[96:111]
	v_mul_f32_e32 v32, v32, v0
	v_mul_f32_e32 v33, v33, v0
	v_mul_f32_e32 v34, v34, v0
	v_mul_f32_e32 v35, v35, v0
	v_mul_f32_e32 v36, v36, v0
	v_mul_f32_e32 v37, v37, v0
	v_mul_f32_e32 v38, v38, v0
	v_mul_f32_e32 v39, v39, v0
	v_cvt_pk_bf16_f32 v6, v32, v33
	v_cvt_pk_bf16_f32 v7, v34, v35
	v_cvt_pk_bf16_f32 v8, v36, v37
	v_cvt_pk_bf16_f32 v9, v38, v39
	s_nop 1
	s_waitcnt vmcnt(15)
	v_mfma_f32_32x32x16_bf16 v[232:247], v[116:119], v[6:9], v[232:247]
	s_waitcnt vmcnt(14)
	v_mfma_f32_32x32x16_bf16 v[96:111], v[112:115], v[6:9], v[96:111]
	v_mul_f32_e32 v40, v40, v0
	v_mul_f32_e32 v41, v41, v0
	v_mul_f32_e32 v42, v42, v0
	v_mul_f32_e32 v43, v43, v0
	v_mul_f32_e32 v44, v44, v0
	v_mul_f32_e32 v45, v45, v0
	v_mul_f32_e32 v46, v46, v0
	v_mul_f32_e32 v47, v47, v0
	v_cvt_pk_bf16_f32 v10, v40, v41
	v_cvt_pk_bf16_f32 v11, v42, v43
	v_cvt_pk_bf16_f32 v12, v44, v45
	v_cvt_pk_bf16_f32 v13, v46, v47
	s_nop 1
	s_waitcnt vmcnt(13)
	v_mfma_f32_32x32x16_bf16 v[232:247], v[220:223], v[10:13], v[232:247]
	s_waitcnt vmcnt(12)
	v_mfma_f32_32x32x16_bf16 v[96:111], v[224:227], v[10:13], v[96:111]
	v_mul_f32_e32 v16, v16, v0
	v_mul_f32_e32 v17, v17, v0
	v_mul_f32_e32 v18, v18, v0
	v_mul_f32_e32 v19, v19, v0
	v_mul_f32_e32 v20, v20, v0
	v_mul_f32_e32 v21, v21, v0
	v_mul_f32_e32 v22, v22, v0
	v_mul_f32_e32 v23, v23, v0
	v_cvt_pk_bf16_f32 v6, v16, v17
	v_cvt_pk_bf16_f32 v7, v18, v19
	v_cvt_pk_bf16_f32 v8, v20, v21
	v_cvt_pk_bf16_f32 v9, v22, v23
	s_nop 1
	s_waitcnt vmcnt(11)
	v_mfma_f32_32x32x16_bf16 v[232:247], v[228:231], v[6:9], v[232:247]
	s_waitcnt vmcnt(10)
	v_mfma_f32_32x32x16_bf16 v[96:111], v[80:83], v[6:9], v[96:111]
	v_mul_f32_e32 v24, v24, v0
	v_mul_f32_e32 v25, v25, v0
	v_mul_f32_e32 v26, v26, v0
	v_mul_f32_e32 v27, v27, v0
	v_mul_f32_e32 v28, v28, v0
	v_mul_f32_e32 v29, v29, v0
	v_mul_f32_e32 v30, v30, v0
	v_mul_f32_e32 v31, v31, v0
	v_cvt_pk_bf16_f32 v10, v24, v25
	v_cvt_pk_bf16_f32 v11, v26, v27
	v_cvt_pk_bf16_f32 v12, v28, v29
	v_cvt_pk_bf16_f32 v13, v30, v31
	s_nop 1
	s_waitcnt vmcnt(9)
	v_mfma_f32_32x32x16_bf16 v[232:247], v[84:87], v[10:13], v[232:247]
	s_waitcnt vmcnt(8)
	v_mfma_f32_32x32x16_bf16 v[96:111], v[88:91], v[10:13], v[96:111]
	v_cmp_gt_u32_e32 vcc, s76, v167
	s_and_saveexec_b64 s[6:7], vcc
	s_cbranch_execz .LBB0_470
	s_nop 10
	s_waitcnt vmcnt(7)
	v_lshlrev_b32_e32 v2, 16, v190
	v_and_b32_e32 v3, 0xffff0000, v190
	v_lshlrev_b32_e32 v4, 16, v191
	v_and_b32_e32 v5, 0xffff0000, v191
	v_mul_f32_e32 v232, v232, v2
	v_mul_f32_e32 v233, v233, v3
	v_mul_f32_e32 v234, v234, v4
	v_mul_f32_e32 v235, v235, v5
	v_cvt_pk_bf16_f32 v190, v232, v233
	v_cvt_pk_bf16_f32 v191, v234, v235
	s_waitcnt vmcnt(6)
	v_lshlrev_b32_e32 v2, 16, v192
	v_and_b32_e32 v3, 0xffff0000, v192
	v_lshlrev_b32_e32 v4, 16, v193
	v_and_b32_e32 v5, 0xffff0000, v193
	v_mul_f32_e32 v236, v236, v2
	v_mul_f32_e32 v237, v237, v3
	v_mul_f32_e32 v238, v238, v4
	v_mul_f32_e32 v239, v239, v5
	v_cvt_pk_bf16_f32 v192, v236, v237
	v_cvt_pk_bf16_f32 v193, v238, v239
	s_waitcnt vmcnt(5)
	v_lshlrev_b32_e32 v2, 16, v194
	v_and_b32_e32 v3, 0xffff0000, v194
	v_lshlrev_b32_e32 v4, 16, v195
	v_and_b32_e32 v5, 0xffff0000, v195
	v_mul_f32_e32 v240, v240, v2
	v_mul_f32_e32 v241, v241, v3
	v_mul_f32_e32 v242, v242, v4
	v_mul_f32_e32 v243, v243, v5
	v_cvt_pk_bf16_f32 v194, v240, v241
	v_cvt_pk_bf16_f32 v195, v242, v243
	s_waitcnt vmcnt(4)
	v_lshlrev_b32_e32 v2, 16, v198
	v_and_b32_e32 v3, 0xffff0000, v198
	v_lshlrev_b32_e32 v4, 16, v199
	v_and_b32_e32 v5, 0xffff0000, v199
	v_mul_f32_e32 v244, v244, v2
	v_mul_f32_e32 v245, v245, v3
	v_mul_f32_e32 v246, v246, v4
	v_mul_f32_e32 v247, v247, v5
	v_cvt_pk_bf16_f32 v198, v244, v245
	v_cvt_pk_bf16_f32 v199, v246, v247
	s_waitcnt vmcnt(3)
	v_lshlrev_b32_e32 v2, 16, v200
	v_and_b32_e32 v3, 0xffff0000, v200
	v_lshlrev_b32_e32 v4, 16, v201
	v_and_b32_e32 v5, 0xffff0000, v201
	v_mul_f32_e32 v96, v96, v2
	v_mul_f32_e32 v97, v97, v3
	v_mul_f32_e32 v98, v98, v4
	v_mul_f32_e32 v99, v99, v5
	v_cvt_pk_bf16_f32 v200, v96, v97
	v_cvt_pk_bf16_f32 v201, v98, v99
	s_waitcnt vmcnt(2)
	v_lshlrev_b32_e32 v2, 16, v202
	v_and_b32_e32 v3, 0xffff0000, v202
	v_lshlrev_b32_e32 v4, 16, v203
	v_and_b32_e32 v5, 0xffff0000, v203
	v_mul_f32_e32 v100, v100, v2
	v_mul_f32_e32 v101, v101, v3
	v_mul_f32_e32 v102, v102, v4
	v_mul_f32_e32 v103, v103, v5
	v_cvt_pk_bf16_f32 v202, v100, v101
	v_cvt_pk_bf16_f32 v203, v102, v103
	s_waitcnt vmcnt(1)
	v_lshlrev_b32_e32 v2, 16, v216
	v_and_b32_e32 v3, 0xffff0000, v216
	v_lshlrev_b32_e32 v4, 16, v217
	v_and_b32_e32 v5, 0xffff0000, v217
	v_mul_f32_e32 v104, v104, v2
	v_mul_f32_e32 v105, v105, v3
	v_mul_f32_e32 v106, v106, v4
	v_mul_f32_e32 v107, v107, v5
	v_cvt_pk_bf16_f32 v216, v104, v105
	v_cvt_pk_bf16_f32 v217, v106, v107
	s_waitcnt vmcnt(0)
	v_lshlrev_b32_e32 v2, 16, v248
	v_and_b32_e32 v3, 0xffff0000, v248
	v_lshlrev_b32_e32 v4, 16, v249
	v_and_b32_e32 v5, 0xffff0000, v249
	v_mul_f32_e32 v108, v108, v2
	v_mul_f32_e32 v109, v109, v3
	v_mul_f32_e32 v110, v110, v4
	v_mul_f32_e32 v111, v111, v5
	v_cvt_pk_bf16_f32 v248, v108, v109
	v_cvt_pk_bf16_f32 v249, v110, v111
	global_store_dwordx2 v212, v[190:191], s[52:53] offset:0
	global_store_dwordx2 v212, v[192:193], s[52:53] offset:16
	global_store_dwordx2 v212, v[194:195], s[52:53] offset:32
	global_store_dwordx2 v212, v[198:199], s[52:53] offset:48
	global_store_dwordx2 v212, v[200:201], s[52:53] offset:64
	global_store_dwordx2 v212, v[202:203], s[52:53] offset:80
	global_store_dwordx2 v212, v[216:217], s[52:53] offset:96
	global_store_dwordx2 v212, v[248:249], s[52:53] offset:112
	s_or_b64 exec, exec, s[6:7]
	s_mov_b64 s[6:7], 0
	s_waitcnt vmcnt(0)
	s_barrier
	s_and_saveexec_b64 s[18:19], s[80:81]
	s_cbranch_execz .Lat3_smpdone
	buffer_wbl2 sc1
	s_waitcnt vmcnt(0)
	v_mov_b32_e32 v2, 0x3900
	v_mov_b32_e32 v3, 1
	global_atomic_add v2, v3, s[78:79]
.Lat3_smpdone:
	s_or_b64 exec, exec, s[18:19]
	s_branch .LBB0_470

.Le4a_call:
	s_and_saveexec_b64 s[6:7], s[80:81]
	s_cbranch_execz .Le4a_ready
	v_mov_b32_e32 v2, 0x3900
.Le4a_poll:
	global_load_dword v3, v2, s[78:79] sc1
	s_waitcnt vmcnt(0)
	v_cmp_gt_u32_e32 vcc, 8, v3
	s_cbranch_vccz .Le4a_ready
	s_sleep 1
	s_branch .Le4a_poll
.Le4a_ready:
	s_or_b64 exec, exec, s[6:7]
	s_barrier
	buffer_inv sc1
	s_waitcnt vmcnt(0)
	s_mov_b32 s101, 1
	s_branch .Le4a_entry
.Le4a_return:
	s_mov_b32 s101, 0
	v_mbcnt_lo_u32_b32 v214, -1, 0
	s_waitcnt vmcnt(0)
	s_barrier
	s_branch .Lp3_setup

.Le4a_entry:
	v_mov_b32_e32 v0, v218
	s_barrier
	s_add_u32 s6, s38, 0xa8a8000
	v_ashrrev_i32_e32 v2, 2, v0
	v_bfe_u32 v3, v0, 4, 2
	v_lshlrev_b32_e32 v4, 3, v0
	v_lshrrev_b32_e32 v5, 5, v2
	s_mov_b32 s2, 0x8200
	s_addc_u32 s7, s39, 0
	v_lshlrev_b32_e32 v1, 1, v0
	v_and_b32_e32 v196, 0x78, v4
	v_mul_lo_u32 v5, v5, s2
	v_mul_u32_u24_e32 v6, 0x410, v3
	v_and_b32_e32 v4, 0x200, v4
	v_and_b32_e32 v0, 15, v0
	s_movk_i32 s2, 0xffe0
	s_add_u32 s8, s38, 0xc928000
	v_add3_u32 v4, v5, v6, v4
	v_lshlrev_b32_e32 v0, 5, v0
	v_and_or_b32 v222, v2, s2, v3
	s_addc_u32 s9, s39, 0
	v_and_b32_e32 v220, 0x80, v1
	s_add_i32 s4, s86, 0xffffff04
	s_cmp_eq_u32 s101, 0
	s_cbranch_scc1 .Le4a_regular
	s_add_i32 s4, s100, 0xffffff00
.Le4a_regular:
	v_mov_b32_e32 v1, 0
	s_mov_b32 s5, s101
	v_add3_u32 v221, v4, v0, 0
	v_add_u32_e32 v223, 0x84, v222
	s_mov_b32 s40, 0x77e8000
	s_mov_b32 s41, 0x53c0000
	s_movk_i32 s52, 0x3000
	s_mov_b64 s[10:11], 0x80
	s_mov_b64 s[12:13], 0x20080
	s_mov_b64 s[14:15], 0x100
	s_mov_b64 s[16:17], 0x20100
	s_mov_b64 s[18:19], 0x180
	s_mov_b64 s[20:21], 0x20180
	s_mov_b64 s[22:23], 0x380
	s_movk_i32 s53, 0x100
	v_mov_b32_e32 v224, 1
	s_branch .LBB0_524

.LBB0_566:
	s_cmp_lg_u32 s101, 0
	s_cbranch_scc1 .Le4a_return
	s_waitcnt vmcnt(0)
	s_barrier
	s_and_saveexec_b64 s[2:3], s[80:81]
	s_cbranch_execz .LBB0_583
	s_mov_b64 s[8:9], exec
	s_lshl_b32 s4, s83, 8
	v_mbcnt_lo_u32_b32 v0, s8, 0
	s_add_u32 s6, s78, s4
	v_mbcnt_hi_u32_b32 v0, s9, v0
	s_addc_u32 s7, s79, 0
	v_cmp_eq_u32_e32 vcc, 0, v0
	s_and_saveexec_b64 s[10:11], vcc
	s_cbranch_execz .LBB0_569
	s_bcnt1_i32_b64 s4, s[8:9]
	v_mov_b32_e32 v1, 0x1000
	v_mov_b32_e32 v2, s4
	global_atomic_add v1, v1, v2, s[6:7] sc0
